# P7 W_down conversion loop software-pipelined (next item's loads issued into a second register bank) and all 4096 items given to the 128 workgroups without a cross-attention unit
# speedup vs baseline: 1.0013x; 1.0013x over previous
.LBB0_1249:
.LBB0_1250:
	s_lshl_b32 s2, s33, 3
	s_cmpk_lt_u32 s33, 0x80
	s_cbranch_scc1 .LBB0_1252
	s_addk_i32 s2, 0xfc00
	s_movk_i32 s5, 0x1000
	s_mov_b32 s0, 0
	s_branch .LBB0_1253
.LBB0_1252:
	s_movk_i32 s5, 0x1000
	s_movk_i32 s0, 0x1000

.Lmy_cv_loop:
	v_add_u32_e32 v132, s4, v8
	v_add_u32_e32 v133, s6, v12
	v_cmp_gt_i32_e32 vcc, s5, v132
	s_cbranch_vccz .Lmy_cv_nonext
	v_ashrrev_i32_e32 v246, 31, v132
	v_lshrrev_b32_e32 v246, 27, v246
	v_add_u32_e32 v246, v132, v246
	v_ashrrev_i32_e32 v246, 5, v246
	v_lshlrev_b32_e32 v247, 11, v246
	v_lshlrev_b32_e32 v246, 6, v246
	v_or_b32_e32 v162, v246, v9
	v_sub_u32_e32 v160, v133, v247
	v_or_b32_e32 v164, 4, v162
	v_or_b32_e32 v166, 8, v162
	v_or_b32_e32 v168, 12, v162
	v_or_b32_e32 v170, 16, v162
	v_or_b32_e32 v172, 20, v162
	v_or_b32_e32 v174, 24, v162
	v_or_b32_e32 v176, 28, v162
	v_or_b32_e32 v178, 32, v162
	v_or_b32_e32 v180, 36, v162
	v_or_b32_e32 v182, 40, v162
	v_or_b32_e32 v184, 44, v162
	v_ashrrev_i32_e32 v161, 31, v160
	v_ashrrev_i32_e32 v163, 31, v162
	v_or_b32_e32 v186, 48, v162
	v_or_b32_e32 v188, 52, v162
	v_or_b32_e32 v190, 56, v162
	v_or_b32_e32 v192, 60, v162
	v_ashrrev_i32_e32 v165, 31, v164
	v_ashrrev_i32_e32 v167, 31, v166
	v_ashrrev_i32_e32 v169, 31, v168
	v_ashrrev_i32_e32 v171, 31, v170
	v_ashrrev_i32_e32 v173, 31, v172
	v_ashrrev_i32_e32 v175, 31, v174
	v_ashrrev_i32_e32 v177, 31, v176
	v_ashrrev_i32_e32 v179, 31, v178
	v_ashrrev_i32_e32 v181, 31, v180
	v_ashrrev_i32_e32 v183, 31, v182
	v_ashrrev_i32_e32 v185, 31, v184
	v_add_u32_e32 v248, v160, v10
	v_lshl_add_u64 v[194:195], v[160:161], 2, v[0:1]
	v_lshlrev_b64 v[160:161], 13, v[162:163]
	v_ashrrev_i32_e32 v187, 31, v186
	v_ashrrev_i32_e32 v189, 31, v188
	v_ashrrev_i32_e32 v191, 31, v190
	v_ashrrev_i32_e32 v193, 31, v192
	v_lshlrev_b64 v[164:165], 13, v[164:165]
	v_lshlrev_b64 v[166:167], 13, v[166:167]
	v_lshlrev_b64 v[168:169], 13, v[168:169]
	v_lshlrev_b64 v[170:171], 13, v[170:171]
	v_lshlrev_b64 v[172:173], 13, v[172:173]
	v_lshlrev_b64 v[174:175], 13, v[174:175]
	v_lshlrev_b64 v[176:177], 13, v[176:177]
	v_lshlrev_b64 v[178:179], 13, v[178:179]
	v_lshlrev_b64 v[180:181], 13, v[180:181]
	v_lshlrev_b64 v[182:183], 13, v[182:183]
	v_lshlrev_b64 v[184:185], 13, v[184:185]
	v_lshl_add_u64 v[160:161], v[194:195], 0, v[160:161]
	v_lshlrev_b64 v[186:187], 13, v[186:187]
	v_lshlrev_b64 v[188:189], 13, v[188:189]
	v_lshlrev_b64 v[190:191], 13, v[190:191]
	v_lshlrev_b64 v[192:193], 13, v[192:193]
	v_lshl_add_u64 v[200:201], v[194:195], 0, v[164:165]
	v_lshl_add_u64 v[202:203], v[194:195], 0, v[166:167]
	v_lshl_add_u64 v[204:205], v[194:195], 0, v[168:169]
	v_lshl_add_u64 v[206:207], v[194:195], 0, v[170:171]
	v_lshl_add_u64 v[208:209], v[194:195], 0, v[172:173]
	v_lshl_add_u64 v[210:211], v[194:195], 0, v[174:175]
	v_lshl_add_u64 v[212:213], v[194:195], 0, v[176:177]
	v_lshl_add_u64 v[214:215], v[194:195], 0, v[178:179]
	v_lshl_add_u64 v[216:217], v[194:195], 0, v[180:181]
	v_lshl_add_u64 v[220:221], v[194:195], 0, v[182:183]
	v_lshl_add_u64 v[222:223], v[194:195], 0, v[184:185]
	global_load_dwordx4 v[160:163], v[160:161], off nt
	v_lshl_add_u64 v[238:239], v[194:195], 0, v[186:187]
	v_lshl_add_u64 v[240:241], v[194:195], 0, v[188:189]
	v_lshl_add_u64 v[242:243], v[194:195], 0, v[190:191]
	v_lshl_add_u64 v[244:245], v[194:195], 0, v[192:193]
	global_load_dwordx4 v[164:167], v[200:201], off nt
	global_load_dwordx4 v[168:171], v[202:203], off nt
	global_load_dwordx4 v[172:175], v[204:205], off nt
	global_load_dwordx4 v[176:179], v[206:207], off nt
	global_load_dwordx4 v[180:183], v[208:209], off nt
	global_load_dwordx4 v[184:187], v[210:211], off nt
	global_load_dwordx4 v[188:191], v[212:213], off nt
	global_load_dwordx4 v[192:195], v[214:215], off nt
	global_load_dwordx4 v[196:199], v[216:217], off nt
	global_load_dwordx4 v[200:203], v[220:221], off nt
	global_load_dwordx4 v[204:207], v[222:223], off nt
	global_load_dwordx4 v[208:211], v[238:239], off nt
	s_nop 0
	global_load_dwordx4 v[212:215], v[240:241], off nt
	global_load_dwordx4 v[216:219], v[242:243], off nt
	global_load_dwordx4 v[220:223], v[244:245], off nt
	s_waitcnt vmcnt(16)
	s_branch .Lmy_cv_wr

.Lmy_cv_wr:
	v_ashrrev_i32_e32 v5, 31, v4
	v_ashrrev_i32_e32 v7, 31, v6
	v_lshl_add_u64 v[4:5], v[4:5], 1, v[2:3]
	v_lshlrev_b64 v[122:123], 14, v[6:7]
	v_add_u32_e32 v110, 8, v6
	v_lshl_add_u64 v[122:123], v[4:5], 0, v[122:123]
	v_ashrrev_i32_e32 v111, 31, v110
	v_lshlrev_b64 v[110:111], 14, v[110:111]
	v_add_u32_e32 v112, 16, v6
	v_lshl_add_u64 v[110:111], v[4:5], 0, v[110:111]
	v_ashrrev_i32_e32 v113, 31, v112
	v_lshlrev_b64 v[112:113], 14, v[112:113]
	v_add_u32_e32 v114, 24, v6
	v_lshl_add_u64 v[112:113], v[4:5], 0, v[112:113]
	ds_write2_b32 v13, v46, v47 offset1:1
	ds_write2_b32 v13, v48, v49 offset0:2 offset1:3
	ds_write2_b32 v14, v50, v51 offset1:1
	ds_write2_b32 v15, v52, v53 offset1:1
	ds_write2_b32 v16, v54, v55 offset1:1
	ds_write2_b32 v17, v56, v57 offset1:1
	ds_write2_b32 v18, v58, v59 offset1:1
	ds_write2_b32 v19, v60, v61 offset1:1
	ds_write2_b32 v20, v62, v63 offset1:1
	ds_write2_b32 v21, v64, v65 offset1:1
	ds_write2_b32 v22, v66, v67 offset1:1
	ds_write2_b32 v23, v68, v69 offset1:1
	ds_write2_b32 v24, v70, v71 offset1:1
	ds_write2_b32 v25, v72, v73 offset1:1
	ds_write2_b32 v26, v74, v75 offset1:1
	ds_write2_b32 v27, v76, v77 offset1:1
	ds_write2_b32 v28, v78, v79 offset1:1
	ds_write2_b32 v29, v80, v81 offset1:1
	ds_write2_b32 v30, v82, v83 offset1:1
	ds_write2_b32 v31, v84, v85 offset1:1
	ds_write2_b32 v32, v86, v87 offset1:1
	ds_write2_b32 v33, v88, v89 offset1:1
	ds_write2_b32 v34, v90, v91 offset1:1
	ds_write2_b32 v35, v92, v93 offset1:1
	ds_write2_b32 v36, v94, v95 offset1:1
	ds_write2_b32 v37, v96, v97 offset1:1
	ds_write2_b32 v38, v98, v99 offset1:1
	ds_write2_b32 v39, v100, v101 offset1:1
	ds_write2_b32 v40, v102, v103 offset1:1
	ds_write2_b32 v41, v104, v105 offset1:1
	ds_write2_b32 v42, v106, v107 offset1:1
	ds_write2_b32 v43, v108, v109 offset1:1
	s_waitcnt lgkmcnt(0)
	ds_read2_b32 v[46:47], v11 offset1:65
	s_waitcnt lgkmcnt(0)
	v_cvt_pk_bf16_f32 v46, v46, v47
	ds_read2_b32 v[48:49], v11 offset0:130 offset1:195
	s_waitcnt lgkmcnt(0)
	v_cvt_pk_bf16_f32 v47, v48, v49
	ds_read2_b32 v[48:49], v44 offset0:4 offset1:69
	s_waitcnt lgkmcnt(0)
	v_cvt_pk_bf16_f32 v48, v48, v49
	ds_read2_b32 v[50:51], v44 offset0:134 offset1:199
	s_waitcnt lgkmcnt(0)
	v_cvt_pk_bf16_f32 v49, v50, v51
	ds_read2_b32 v[50:51], v11 offset0:8 offset1:73
	global_store_dwordx4 v[122:123], v[46:49], off
	v_ashrrev_i32_e32 v115, 31, v114
	v_lshlrev_b64 v[114:115], 14, v[114:115]
	s_waitcnt lgkmcnt(0)
	v_cvt_pk_bf16_f32 v46, v50, v51
	ds_read2_b32 v[48:49], v11 offset0:138 offset1:203
	s_waitcnt lgkmcnt(0)
	v_cvt_pk_bf16_f32 v47, v48, v49
	ds_read2_b32 v[48:49], v44 offset0:12 offset1:77
	s_waitcnt lgkmcnt(0)
	v_cvt_pk_bf16_f32 v48, v48, v49
	ds_read2_b32 v[50:51], v44 offset0:142 offset1:207
	s_waitcnt lgkmcnt(0)
	v_cvt_pk_bf16_f32 v49, v50, v51
	ds_read2_b32 v[50:51], v11 offset0:16 offset1:81
	global_store_dwordx4 v[110:111], v[46:49], off
	v_add_u32_e32 v116, 32, v6
	v_lshl_add_u64 v[114:115], v[4:5], 0, v[114:115]
	s_waitcnt lgkmcnt(0)
	v_cvt_pk_bf16_f32 v46, v50, v51
	ds_read2_b32 v[48:49], v11 offset0:146 offset1:211
	s_waitcnt lgkmcnt(0)
	v_cvt_pk_bf16_f32 v47, v48, v49
	ds_read2_b32 v[48:49], v44 offset0:20 offset1:85
	s_waitcnt lgkmcnt(0)
	v_cvt_pk_bf16_f32 v48, v48, v49
	ds_read2_b32 v[50:51], v44 offset0:150 offset1:215
	s_waitcnt lgkmcnt(0)
	v_cvt_pk_bf16_f32 v49, v50, v51
	ds_read2_b32 v[50:51], v11 offset0:24 offset1:89
	global_store_dwordx4 v[112:113], v[46:49], off
	v_ashrrev_i32_e32 v117, 31, v116
	v_lshlrev_b64 v[116:117], 14, v[116:117]
	s_waitcnt lgkmcnt(0)
	v_cvt_pk_bf16_f32 v46, v50, v51
	ds_read2_b32 v[48:49], v11 offset0:154 offset1:219
	s_waitcnt lgkmcnt(0)
	v_cvt_pk_bf16_f32 v47, v48, v49
	ds_read2_b32 v[48:49], v44 offset0:28 offset1:93
	s_waitcnt lgkmcnt(0)
	v_cvt_pk_bf16_f32 v48, v48, v49
	ds_read2_b32 v[50:51], v44 offset0:158 offset1:223
	s_waitcnt lgkmcnt(0)
	v_cvt_pk_bf16_f32 v49, v50, v51
	ds_read2_b32 v[50:51], v11 offset0:32 offset1:97
	global_store_dwordx4 v[114:115], v[46:49], off
	v_add_u32_e32 v118, 40, v6
	v_lshl_add_u64 v[116:117], v[4:5], 0, v[116:117]
	s_waitcnt lgkmcnt(0)
	v_cvt_pk_bf16_f32 v46, v50, v51
	ds_read2_b32 v[48:49], v11 offset0:162 offset1:227
	s_waitcnt lgkmcnt(0)
	v_cvt_pk_bf16_f32 v47, v48, v49
	ds_read2_b32 v[48:49], v44 offset0:36 offset1:101
	s_waitcnt lgkmcnt(0)
	v_cvt_pk_bf16_f32 v48, v48, v49
	ds_read2_b32 v[50:51], v44 offset0:166 offset1:231
	s_waitcnt lgkmcnt(0)
	v_cvt_pk_bf16_f32 v49, v50, v51
	v_ashrrev_i32_e32 v119, 31, v118
	ds_read2_b32 v[50:51], v11 offset0:40 offset1:105
	global_store_dwordx4 v[116:117], v[46:49], off
	v_lshlrev_b64 v[118:119], 14, v[118:119]
	v_add_u32_e32 v120, 48, v6
	s_waitcnt lgkmcnt(0)
	v_cvt_pk_bf16_f32 v46, v50, v51
	ds_read2_b32 v[48:49], v11 offset0:170 offset1:235
	s_waitcnt lgkmcnt(0)
	v_cvt_pk_bf16_f32 v47, v48, v49
	ds_read2_b32 v[48:49], v44 offset0:44 offset1:109
	v_lshl_add_u64 v[118:119], v[4:5], 0, v[118:119]
	s_waitcnt lgkmcnt(0)
	v_cvt_pk_bf16_f32 v48, v48, v49
	ds_read2_b32 v[50:51], v44 offset0:174 offset1:239
	s_waitcnt lgkmcnt(0)
	v_cvt_pk_bf16_f32 v49, v50, v51
	v_ashrrev_i32_e32 v121, 31, v120
	ds_read2_b32 v[50:51], v11 offset0:48 offset1:113
	global_store_dwordx4 v[118:119], v[46:49], off
	v_lshlrev_b64 v[120:121], 14, v[120:121]
	v_add_u32_e32 v6, 56, v6
	s_waitcnt lgkmcnt(0)
	v_cvt_pk_bf16_f32 v46, v50, v51
	ds_read2_b32 v[48:49], v11 offset0:178 offset1:243
	s_waitcnt lgkmcnt(0)
	v_cvt_pk_bf16_f32 v47, v48, v49
	ds_read2_b32 v[48:49], v44 offset0:52 offset1:117
	v_lshl_add_u64 v[120:121], v[4:5], 0, v[120:121]
	s_waitcnt lgkmcnt(0)
	v_cvt_pk_bf16_f32 v48, v48, v49
	ds_read2_b32 v[50:51], v44 offset0:182 offset1:247
	s_waitcnt lgkmcnt(0)
	v_cvt_pk_bf16_f32 v49, v50, v51
	v_ashrrev_i32_e32 v7, 31, v6
	ds_read2_b32 v[50:51], v11 offset0:56 offset1:121
	global_store_dwordx4 v[120:121], v[46:49], off
	v_lshlrev_b64 v[6:7], 14, v[6:7]
	v_lshl_add_u64 v[4:5], v[4:5], 0, v[6:7]
	s_waitcnt lgkmcnt(0)
	v_cvt_pk_bf16_f32 v46, v50, v51
	ds_read2_b32 v[48:49], v11 offset0:186 offset1:251
	s_waitcnt lgkmcnt(0)
	v_cvt_pk_bf16_f32 v47, v48, v49
	ds_read2_b32 v[48:49], v44 offset0:60 offset1:125
	s_waitcnt lgkmcnt(0)
	v_cvt_pk_bf16_f32 v48, v48, v49
	ds_read2_b32 v[50:51], v44 offset0:190 offset1:255
	s_waitcnt lgkmcnt(0)
	v_cvt_pk_bf16_f32 v49, v50, v51
	global_store_dwordx4 v[4:5], v[46:49], off
	s_waitcnt lgkmcnt(0)
	v_cmp_gt_i32_e32 vcc, s5, v132
	s_cbranch_vccz .LBB0_1257
	s_waitcnt vmcnt(8)
	v_mov_b32_e32 v46, v160
	v_mov_b32_e32 v47, v161
	v_mov_b32_e32 v48, v162
	v_mov_b32_e32 v49, v163
	v_mov_b32_e32 v50, v164
	v_mov_b32_e32 v51, v165
	v_mov_b32_e32 v52, v166
	v_mov_b32_e32 v53, v167
	v_mov_b32_e32 v54, v168
	v_mov_b32_e32 v55, v169
	v_mov_b32_e32 v56, v170
	v_mov_b32_e32 v57, v171
	v_mov_b32_e32 v58, v172
	v_mov_b32_e32 v59, v173
	v_mov_b32_e32 v60, v174
	v_mov_b32_e32 v61, v175
	v_mov_b32_e32 v62, v176
	v_mov_b32_e32 v63, v177
	v_mov_b32_e32 v64, v178
	v_mov_b32_e32 v65, v179
	v_mov_b32_e32 v66, v180
	v_mov_b32_e32 v67, v181
	v_mov_b32_e32 v68, v182
	v_mov_b32_e32 v69, v183
	v_mov_b32_e32 v70, v184
	v_mov_b32_e32 v71, v185
	v_mov_b32_e32 v72, v186
	v_mov_b32_e32 v73, v187
	v_mov_b32_e32 v74, v188
	v_mov_b32_e32 v75, v189
	v_mov_b32_e32 v76, v190
	v_mov_b32_e32 v77, v191
	v_mov_b32_e32 v78, v192
	v_mov_b32_e32 v79, v193
	v_mov_b32_e32 v80, v194
	v_mov_b32_e32 v81, v195
	v_mov_b32_e32 v82, v196
	v_mov_b32_e32 v83, v197
	v_mov_b32_e32 v84, v198
	v_mov_b32_e32 v85, v199
	v_mov_b32_e32 v86, v200
	v_mov_b32_e32 v87, v201
	v_mov_b32_e32 v88, v202
	v_mov_b32_e32 v89, v203
	v_mov_b32_e32 v90, v204
	v_mov_b32_e32 v91, v205
	v_mov_b32_e32 v92, v206
	v_mov_b32_e32 v93, v207
	v_mov_b32_e32 v94, v208
	v_mov_b32_e32 v95, v209
	v_mov_b32_e32 v96, v210
	v_mov_b32_e32 v97, v211
	v_mov_b32_e32 v98, v212
	v_mov_b32_e32 v99, v213
	v_mov_b32_e32 v100, v214
	v_mov_b32_e32 v101, v215
	v_mov_b32_e32 v102, v216
	v_mov_b32_e32 v103, v217
	v_mov_b32_e32 v104, v218
	v_mov_b32_e32 v105, v219
	v_mov_b32_e32 v106, v220
	v_mov_b32_e32 v107, v221
	v_mov_b32_e32 v108, v222
	v_mov_b32_e32 v109, v223
	v_mov_b32_e32 v4, v246
	v_mov_b32_e32 v6, v248
	v_mov_b32_e32 v8, v132
	v_mov_b32_e32 v12, v133
	s_branch .Lmy_cv_loop
